# attention queues: 1:1 prompt/decode for 96 tickets, then the last 16 decode units, then the 16 shortest prompts
# baseline (speedup 1.0000x reference)
; __device__ __forceinline__ int fresh_lane() { int l; asm volatile("v_mbcnt_lo_u32_b32 %0, -1, 0\n\tv_mbcnt_hi_u32_b32 %0, -1, %0" : "=v"(l)); return l; }
; #define SEAM(k) do { if (IN(k) && IN((k) + 1)) xcd_barrier(bar, C.wave); } while (0)
; #define PH5 { phase_attention(P, C, (P.pad >> 8) & 3, P.li); }
; #define RUN(k, BODY) do { if (IN(k)) { unsigned char* ws = P.ws; LAUNDER_GPTR(ws); BODY } } while (0)
; __device__ __forceinline__ void phase_attention(const Params& P, const Ctx& C, int parts, int qset) {
;     ...
;     for (int i = 0; i < 8; ++i) { const int x = (x0 + i) & 7;
;         for (;;) {
;             __syncthreads();
;             if (C.wave == 0 && fresh_lane() == 0) *slot = __hip_atomic_fetch_add(qc + 64 * x, 1u, __ATOMIC_RELAXED, __HIP_MEMORY_SCOPE_AGENT);
;             __syncthreads();
;             const unsigned u = *slot;
;             if (u >= 128u) break;
;             const int us = __builtin_amdgcn_readfirstlane((int)u);
; __global__ void __launch_bounds__(NWAVES * 64, 2) fwd_kernel(Params P) {
;     ...
;     RUN(3, PH3); SEAM(3);
;     RUN(4, PH4);
;     RUN(5, PH5); SEAM(5);
.LBB0_1136:
	s_bitcmp1_b32 s101, 1
	s_cbranch_scc1 .Lmy_e7
	s_bitset1_b32 s101, 1
	s_cmpk_lg_i32 s68, 0x100
	s_cbranch_scc1 .Lmy_e7
	s_bitset1_b32 s101, 3
	v_readlane_b32 s99, v254, 10
	s_cmpk_lt_u32 s99, 192
	s_cbranch_scc1 .Lmy_e7
	s_and_b32 s100, s99, 31
	s_lshl_b32 vcc_lo, s100, 1
	s_add_i32 vcc_lo, vcc_lo, 48
	s_lshl_b32 vcc_hi, s100, 2
	s_add_i32 vcc_hi, vcc_hi, 1
	s_cmpk_lt_u32 s100, 24
	s_cselect_b32 s100, vcc_hi, vcc_lo
	s_bitset1_b32 s101, 0
	s_waitcnt vmcnt(0)
	s_barrier
	s_mov_b64 s[2:3], -1
	s_branch .LBB0_1192

; __device__ __forceinline__ int fresh_lane() { int l; asm volatile("v_mbcnt_lo_u32_b32 %0, -1, 0\n\tv_mbcnt_hi_u32_b32 %0, -1, %0" : "=v"(l)); return l; }
; __device__ __forceinline__ void phase_attention(const Params& P, const Ctx& C, int parts, int qset) {
;     ...
;             __syncthreads();
;             if (C.wave == 0 && fresh_lane() == 0) *slot = __hip_atomic_fetch_add(qc + 64 * x, 1u, __ATOMIC_RELAXED, __HIP_MEMORY_SCOPE_AGENT);
;             __syncthreads();
;             const unsigned u = *slot;
;             if (u >= 128u) break;
;             const int us = __builtin_amdgcn_readfirstlane((int)u);
;             int pq = -1, dq = -1;
;             if (us < 96) { const int k = us / 3, r = us - 3 * k; if (r == 0) pq = 63 - k; else dq = 2 * k + r - 1; } else pq = 127 - us;
.LBB0_1208:
	s_waitcnt lgkmcnt(0)
	s_barrier
	ds_read_b32 v0, v218
	s_movk_i32 s2, 0x7f
	s_waitcnt lgkmcnt(0)
	v_cmp_lt_u32_e32 vcc, s2, v0
	s_mov_b64 s[2:3], -1
	s_cbranch_vccnz .LBB0_1201
	v_readfirstlane_b32 s5, v0
	s_cmpk_gt_i32 s5, 111
	s_cbranch_scc1 .LBB0_1213
	s_andn2_b64 vcc, exec, s[2:3]
	s_mov_b32 s4, -1
	s_cbranch_vccz .LBB0_1214

; __device__ __forceinline__ void phase_attention(const Params& P, const Ctx& C, int parts, int qset) {
;     ...
;             const int us = __builtin_amdgcn_readfirstlane((int)u);
;             int pq = -1, dq = -1;
;             if (us < 96) { const int k = us / 3, r = us - 3 * k; if (r == 0) pq = 63 - k; else dq = 2 * k + r - 1; } else pq = 127 - us;
;             if (pq >= 0) { if (parts & 1) { if (fixed_ok) attn_prompt_unit<true>(P, C, x, pq); else attn_prompt_unit<false>(P, C, x, pq); } }
.LBB0_1214:
	s_lshr_b32 s2, s5, 1
	s_and_b32 s3, s5, 1
	s_sub_i32 s4, 63, s2
	s_cmp_eq_u32 s3, 0
	s_cselect_b32 s64, s4, -1
	s_cselect_b32 s4, -1, s2
	s_add_i32 s3, s5, -48
	s_cmpk_gt_i32 s5, 95
	s_cselect_b32 s64, -1, s64
	s_cselect_b32 s4, s3, s4
	s_cmp_lt_i32 s64, 0
	s_mov_b64 s[2:3], -1
	s_cbranch_scc0 .LBB0_1212
